# grid barrier: acquire invalidate issued at arrival (overlaps the wait); mamba dt_bias/a_log prefetched with next-unit inputs
# speedup vs baseline: 1.0529x; 1.0075x over previous
; __device__ __forceinline__ void mamba_block(ArgsP a_, unsigned char* smem) { const ArgsP a = a_;
;     ...
;         if (tid < 64) { const int j = tid; const bool valid = j < len; const float dtr = dtpre + AIN(22)[hd];
;             const float dt = valid ? (dtr > 20.f ? dtr : log1pf(__expf(dtr))) : 0.f; float x = -dt * __expf(AIN(23)[hd]);
.LBB0_318:
	s_lshl_b32 s22, s35, 6
	s_and_b32 s61, s35, 31
	s_and_b32 s22, s22, 0x700
	v_readlane_b32 s42, v255, 12
	v_lshlrev_b32_e32 v0, 4, v57
	v_ashrrev_i32_e32 v10, 4, v57
	v_readlane_b32 s43, v255, 13
	s_add_u32 s40, s42, s22
	v_and_b32_e32 v16, 0xf0, v0
	v_add_u32_e32 v0, s60, v10
	s_addc_u32 s41, s43, 0
	v_ashrrev_i32_e32 v1, 31, v0
	v_lshl_add_u64 v[8:9], s[40:41], 0, v[16:17]
	v_lshlrev_b64 v[0:1], 13, v[0:1]
	v_lshl_add_u64 v[0:1], v[8:9], 0, v[0:1]
	s_movk_i32 s22, 0x1000
	v_add_co_u32_e32 v4, vcc, s22, v0
	v_lshlrev_b32_e32 v30, 3, v19
	s_nop 0
	v_addc_co_u32_e32 v5, vcc, 0, v1, vcc
	v_cmp_gt_i32_e32 vcc, s34, v10
	v_add_u32_e32 v10, 0x200, v57
	v_ashrrev_i32_e32 v16, 4, v10
	v_add_u32_e32 v10, s60, v16
	v_ashrrev_i32_e32 v11, 31, v10
	v_lshlrev_b64 v[10:11], 13, v[10:11]
	v_lshl_add_u64 v[8:9], v[8:9], 0, v[10:11]
	v_add_co_u32_e64 v12, s[40:41], s22, v8
	s_lshl_b32 s22, s61, 7
	s_nop 0
	v_addc_co_u32_e64 v13, s[40:41], 0, v9, s[40:41]
	s_add_u32 s42, s42, s22
	v_add_u32_e32 v20, s60, v30
	v_cmp_gt_i32_e64 s[40:41], s34, v16
	s_addc_u32 s43, s43, 0
	v_lshlrev_b32_e32 v16, 1, v18
	v_ashrrev_i32_e32 v21, 31, v20
	v_lshl_add_u64 v[26:27], s[42:43], 0, v[16:17]
	v_lshlrev_b64 v[20:21], 13, v[20:21]
	v_lshl_add_u64 v[20:21], v[26:27], 0, v[20:21]
	v_or_b32_e32 v22, 1, v30
	v_or_b32_e32 v24, 2, v30
	global_load_dwordx4 v[0:3], v[4:5], off
	s_nop 0
	global_load_dwordx4 v[4:7], v[4:5], off offset:2048
	s_nop 0
	global_load_dwordx4 v[8:11], v[12:13], off
	s_nop 0
	global_load_dwordx4 v[12:15], v[12:13], off offset:2048
	v_cmp_gt_i32_e64 s[44:45], s34, v22
	global_load_ushort v16, v[20:21], off
	v_add_u32_e32 v20, s60, v22
	v_add_u32_e32 v22, s60, v24
	v_ashrrev_i32_e32 v21, 31, v20
	v_ashrrev_i32_e32 v23, 31, v22
	v_lshlrev_b64 v[20:21], 13, v[20:21]
	v_lshlrev_b64 v[22:23], 13, v[22:23]
	v_lshl_add_u64 v[20:21], v[26:27], 0, v[20:21]
	v_lshl_add_u64 v[22:23], v[26:27], 0, v[22:23]
	v_cmp_gt_i32_e64 s[46:47], s34, v24
	v_or_b32_e32 v24, 3, v30
	v_or_b32_e32 v28, 4, v30
	global_load_ushort v20, v[20:21], off
	v_cmp_gt_i32_e64 s[48:49], s34, v24
	global_load_ushort v21, v[22:23], off
	v_add_u32_e32 v22, s60, v24
	v_add_u32_e32 v24, s60, v28
	v_ashrrev_i32_e32 v23, 31, v22
	v_ashrrev_i32_e32 v25, 31, v24
	v_lshlrev_b64 v[22:23], 13, v[22:23]
	v_lshlrev_b64 v[24:25], 13, v[24:25]
	v_lshl_add_u64 v[22:23], v[26:27], 0, v[22:23]
	v_lshl_add_u64 v[24:25], v[26:27], 0, v[24:25]
	v_cmp_gt_i32_e64 s[50:51], s34, v28
	v_or_b32_e32 v28, 5, v30
	v_or_b32_e32 v31, 6, v30
	global_load_ushort v22, v[22:23], off
	v_cmp_gt_i32_e64 s[52:53], s34, v28
	global_load_ushort v23, v[24:25], off
	v_add_u32_e32 v24, s60, v28
	v_add_u32_e32 v28, s60, v31
	v_ashrrev_i32_e32 v25, 31, v24
	v_ashrrev_i32_e32 v29, 31, v28
	v_lshlrev_b64 v[24:25], 13, v[24:25]
	v_lshlrev_b64 v[28:29], 13, v[28:29]
	v_cmp_gt_i32_e64 s[42:43], s34, v30
	v_lshl_add_u64 v[24:25], v[26:27], 0, v[24:25]
	v_lshl_add_u64 v[28:29], v[26:27], 0, v[28:29]
	v_or_b32_e32 v30, 7, v30
	global_load_ushort v24, v[24:25], off
	v_cmp_gt_i32_e64 s[54:55], s34, v31
	global_load_ushort v25, v[28:29], off
	v_add_u32_e32 v28, s60, v30
	v_ashrrev_i32_e32 v29, 31, v28
	v_lshlrev_b64 v[28:29], 13, v[28:29]
	v_lshl_add_u64 v[26:27], v[26:27], 0, v[28:29]
	global_load_ushort v26, v[26:27], off
	v_cmp_gt_i32_e64 s[56:57], s34, v30
	v_cmp_gt_i32_e64 s[58:59], 64, v57
	v_mov_b32_e32 v67, 0
	s_and_saveexec_b64 s[34:35], s[58:59]
	s_cbranch_execz .LBB0_320
	v_add_u32_e32 v28, s60, v57
	v_ashrrev_i32_e32 v29, 31, v28
	v_readlane_b32 s22, v255, 28
	v_lshlrev_b64 v[28:29], 10, v[28:29]
	v_readlane_b32 s23, v255, 29
	s_lshl_b32 s58, s61, 2
	s_mov_b32 s59, s12
	v_lshl_add_u64 v[28:29], s[22:23], 0, v[28:29]
	v_lshl_add_u64 v[28:29], v[28:29], 0, s[58:59]
	global_load_dword v67, v[28:29], off
	s_load_dwordx4 s[84:87], s[4:5], 0xb0
	s_lshl_b32 s22, s61, 2
	v_mov_b32_e32 v28, s22
	s_waitcnt lgkmcnt(0)
	global_load_dword v128, v28, s[84:85]
	global_load_dword v129, v28, s[86:87]

; __device__ __forceinline__ void mamba_block(ArgsP a_, unsigned char* smem) { const ArgsP a = a_;
;     ...
;         for (int e = 0; e < 2; ++e) { const int idx = tid + 512 * e, i = idx >> 4, cc = idx & 15; *(u32x4*)(KB + i * LQ + 8 * cc) = bpre[e]; *(u32x4*)(QA + i * LQ + 8 * cc) = cpre[e]; }
;         if (tid < 64) { const int j = tid; const bool valid = j < len; const float dtr = dtpre + AIN(22)[hd];
;             const float dt = valid ? (dtr > 20.f ? dtr : log1pf(__expf(dtr))) : 0.f; float x = -dt * __expf(AIN(23)[hd]);
.LBB0_342:
	ds_write_b128 v72, v[0:3] offset:17408
	ds_write_b128 v72, v[4:7]
	ds_write_b128 v74, v[8:11] offset:17408
	ds_write_b128 v74, v[12:15]
	s_and_saveexec_b64 s[74:75], s[40:41]
	s_cbranch_execz .LBB0_348
	v_cmp_gt_i32_e32 vcc, s73, v57
	v_mov_b32_e32 v16, 0
	s_and_saveexec_b64 s[76:77], vcc
	s_cbranch_execz .LBB0_347
	s_mov_b32 s22, 0x41a00000
	v_mov_b32_e32 v16, v128
	v_add_f32_e32 v16, v67, v16
	v_cmp_nlt_f32_e32 vcc, s22, v16
	s_and_saveexec_b64 s[78:79], vcc
	s_cbranch_execz .LBB0_346
	v_mul_f32_e32 v16, 0x3fb8aa3b, v16
	v_exp_f32_e32 v16, v16
	s_mov_b32 s22, 0x3f2aaaab
	v_add_f32_e32 v36, 1.0, v16
	v_frexp_mant_f32_e32 v38, v36
	v_cvt_f64_f32_e32 v[18:19], v36
	v_frexp_exp_i32_f64_e32 v18, v[18:19]
	v_cmp_gt_f32_e32 vcc, s22, v38
	v_add_f32_e32 v37, -1.0, v36
	v_sub_f32_e32 v39, v37, v36
	v_subbrev_co_u32_e32 v42, vcc, 0, v18, vcc
	v_sub_u32_e32 v18, 0, v42
	v_sub_f32_e32 v37, v16, v37
	v_add_f32_e32 v39, 1.0, v39
	v_ldexp_f32 v19, v36, v18
	v_add_f32_e32 v37, v37, v39
	v_add_f32_e32 v36, -1.0, v19
	v_add_f32_e32 v38, 1.0, v19
	v_ldexp_f32 v18, v37, v18
	v_add_f32_e32 v37, 1.0, v36
	v_add_f32_e32 v39, -1.0, v38
	v_sub_f32_e32 v37, v19, v37
	v_sub_f32_e32 v19, v19, v39
	v_add_f32_e32 v37, v18, v37
	v_add_f32_e32 v18, v18, v19
	v_add_f32_e32 v43, v38, v18
	v_rcp_f32_e32 v45, v43
	v_sub_f32_e32 v19, v43, v38
	v_sub_f32_e32 v44, v18, v19
	v_add_f32_e32 v19, v36, v37
	v_mul_f32_e32 v47, v19, v45
	v_sub_f32_e32 v18, v19, v36
	v_mul_f32_e32 v36, v43, v47
	v_fma_f32 v38, v47, v43, -v36
	v_fmac_f32_e32 v38, v47, v44
	v_sub_f32_e32 v46, v37, v18
	v_add_f32_e32 v18, v36, v38
	v_sub_f32_e32 v37, v19, v18
	v_pk_add_f32 v[40:41], v[18:19], v[36:37] neg_lo:[0,1] neg_hi:[0,1]
	v_mov_b32_e32 v39, v18
	v_pk_add_f32 v[18:19], v[40:41], v[38:39] neg_lo:[0,1] neg_hi:[0,1]
	s_mov_b32 s22, 0x3f317218
	v_add_f32_e32 v19, v46, v19
	v_add_f32_e32 v18, v18, v19
	v_add_f32_e32 v19, v37, v18
	v_mul_f32_e32 v46, v45, v19
	v_mul_f32_e32 v36, v43, v46
	v_fma_f32 v38, v46, v43, -v36
	v_fmac_f32_e32 v38, v46, v44
	v_sub_f32_e32 v37, v37, v19
	v_add_f32_e32 v43, v18, v37
	v_add_f32_e32 v18, v36, v38
	v_sub_f32_e32 v37, v19, v18
	v_pk_add_f32 v[40:41], v[18:19], v[36:37] neg_lo:[0,1] neg_hi:[0,1]
	v_mov_b32_e32 v39, v18
	v_pk_add_f32 v[18:19], v[40:41], v[38:39] neg_lo:[0,1] neg_hi:[0,1]
	v_cmp_neq_f32_e32 vcc, s37, v16
	v_add_f32_e32 v19, v43, v19
	v_add_f32_e32 v18, v18, v19
	v_add_f32_e32 v19, v47, v46
	v_add_f32_e32 v18, v37, v18
	v_sub_f32_e32 v36, v19, v47
	v_mul_f32_e32 v18, v45, v18
	v_sub_f32_e32 v36, v46, v36
	v_add_f32_e32 v36, v36, v18
	v_add_f32_e32 v38, v19, v36
	v_mul_f32_e32 v39, v38, v38
	v_mov_b32_e32 v18, 0x3ecc95a3
	v_fmamk_f32 v18, v39, 0x3e9b6dac, v18
	v_fmaak_f32 v147, v39, v18, 0x3f2aaada
	v_cvt_f32_i32_e32 v18, v42
	v_sub_f32_e32 v19, v38, v19
	v_sub_f32_e32 v19, v36, v19
	v_ldexp_f32 v40, v19, 1
	v_mul_f32_e32 v19, v38, v39
	v_ldexp_f32 v37, v38, 1
	v_pk_mul_f32 v[38:39], v[18:19], v[146:147]
	s_nop 0
	v_fma_f32 v36, v18, s22, -v38
	v_fmac_f32_e32 v36, 0xb102e308, v18
	v_pk_add_f32 v[18:19], v[38:39], v[36:37]
	s_mov_b32 s22, 0x33800000
	v_sub_f32_e32 v37, v19, v37
	v_sub_f32_e32 v37, v39, v37
	v_add_f32_e32 v41, v40, v37
	v_mov_b32_e32 v40, v38
	v_pk_add_f32 v[38:39], v[18:19], v[38:39] neg_lo:[0,1] neg_hi:[0,1]
	v_pk_add_f32 v[42:43], v[18:19], v[40:41]
	v_mov_b32_e32 v37, v18
	v_mov_b32_e32 v39, v43
	v_pk_add_f32 v[44:45], v[36:37], v[38:39] neg_lo:[0,1] neg_hi:[0,1]
	v_pk_add_f32 v[36:37], v[36:37], v[38:39]
	v_mov_b32_e32 v40, v41
	v_pk_add_f32 v[38:39], v[36:37], v[18:19] op_sel:[1,0] op_sel_hi:[0,1] neg_lo:[0,1] neg_hi:[0,1]
	v_pk_add_f32 v[46:47], v[42:43], v[38:39] op_sel_hi:[1,0] neg_lo:[0,1] neg_hi:[0,1]
	v_mov_b32_e32 v42, v43
	v_mov_b32_e32 v43, v37
	v_pk_mov_b32 v[38:39], v[18:19], v[38:39] op_sel:[1,0]
	v_mov_b32_e32 v41, v18
	v_pk_add_f32 v[38:39], v[42:43], v[38:39] neg_lo:[0,1] neg_hi:[0,1]
	v_mov_b32_e32 v46, v44
	v_pk_add_f32 v[18:19], v[40:41], v[38:39] neg_lo:[0,1] neg_hi:[0,1]
	v_mov_b32_e32 v45, v37
	v_pk_add_f32 v[38:39], v[46:47], v[18:19]
	s_nop 0
	v_pk_add_f32 v[40:41], v[38:39], v[38:39] op_sel:[0,1] op_sel_hi:[1,0]
	s_nop 0
	v_pk_add_f32 v[36:37], v[36:37], v[40:41] op_sel:[1,0] op_sel_hi:[0,1]
	v_mov_b32_e32 v39, v36
	v_pk_add_f32 v[42:43], v[38:39], v[44:45] neg_lo:[0,1] neg_hi:[0,1]
	v_mov_b32_e32 v19, v40
	v_sub_f32_e32 v37, v38, v42
	v_pk_add_f32 v[18:19], v[18:19], v[42:43] neg_lo:[0,1] neg_hi:[0,1]
	v_sub_f32_e32 v37, v44, v37
	v_add_f32_e32 v18, v18, v37
	v_add_f32_e32 v18, v18, v19
	v_add_f32_e32 v18, v36, v18
	v_mov_b32_e32 v19, 0x7f800000
	v_cndmask_b32_e32 v18, v19, v18, vcc
	v_cmp_ngt_f32_e32 vcc, -1.0, v16
	v_mov_b32_e32 v19, 0x7fc00000
	s_nop 0
	v_cndmask_b32_e32 v18, v19, v18, vcc
	v_cmp_neq_f32_e32 vcc, -1.0, v16
	v_mov_b32_e32 v19, 0xff800000
	s_nop 0
	v_cndmask_b32_e32 v18, v19, v18, vcc
	v_cmp_lt_f32_e64 vcc, |v16|, s22
	s_nop 1
	v_cndmask_b32_e32 v16, v18, v16, vcc

; __device__ __forceinline__ void mamba_block(ArgsP a_, unsigned char* smem) { const ArgsP a = a_;
;     ...
;             const float dt = valid ? (dtr > 20.f ? dtr : log1pf(__expf(dtr))) : 0.f; float x = -dt * __expf(AIN(23)[hd]);
; #pragma unroll
;             for (int off = 1; off < 64; off <<= 1) { const float t = __shfl_up(x, off); if (lane >= off) x += t; }
;             const float glast = __shfl(x, 63); GI[j] = x; DTV[j] = dt; W2[j] = dt * __expf(glast - x); const float ed = __expf(glast); SDEC[2 * j] = ed; SDEC[2 * j + 1] = ed; }
.LBB0_347:
	s_or_b64 exec, exec, s[76:77]
	v_and_b32_e32 v36, 64, v188
	v_add_u32_e32 v37, -1, v188
	v_cmp_lt_i32_e32 vcc, v37, v36
	v_readlane_b32 s22, v255, 16
	v_readlane_b32 s23, v255, 17
	v_cndmask_b32_e32 v37, v37, v188, vcc
	v_lshlrev_b32_e32 v37, 2, v37
	v_mul_f32_e32 v18, 0x3fb8aa3b, v129
	v_exp_f32_e32 v18, v18
	s_nop 0
	v_mul_f32_e64 v19, v18, -v16
	ds_bpermute_b32 v37, v37, v19
	s_waitcnt lgkmcnt(0)
	v_fma_f32 v18, v18, -v16, v37
	v_cndmask_b32_e64 v18, v18, v19, s[22:23]
	v_add_u32_e32 v19, -2, v188
	v_cmp_lt_i32_e32 vcc, v19, v36
	v_readlane_b32 s22, v255, 18
	v_readlane_b32 s23, v255, 19
	v_cndmask_b32_e32 v19, v19, v188, vcc
	v_lshlrev_b32_e32 v19, 2, v19
	ds_bpermute_b32 v19, v19, v18
	s_waitcnt lgkmcnt(0)
	v_add_f32_e32 v19, v18, v19
	v_cndmask_b32_e64 v18, v19, v18, s[22:23]
	v_add_u32_e32 v19, -4, v188
	v_cmp_lt_i32_e32 vcc, v19, v36
	v_readlane_b32 s22, v255, 20
	v_readlane_b32 s23, v255, 21
	v_cndmask_b32_e32 v19, v19, v188, vcc
	v_lshlrev_b32_e32 v19, 2, v19
	ds_bpermute_b32 v19, v19, v18
	s_waitcnt lgkmcnt(0)
	v_add_f32_e32 v19, v18, v19
	v_cndmask_b32_e64 v18, v19, v18, s[22:23]
	v_add_u32_e32 v19, -8, v188
	v_cmp_lt_i32_e32 vcc, v19, v36
	v_readlane_b32 s22, v255, 22
	v_readlane_b32 s23, v255, 23
	v_cndmask_b32_e32 v19, v19, v188, vcc
	v_lshlrev_b32_e32 v19, 2, v19
	ds_bpermute_b32 v19, v19, v18
	s_waitcnt lgkmcnt(0)
	v_add_f32_e32 v19, v18, v19
	v_cndmask_b32_e64 v18, v19, v18, s[22:23]
	v_add_u32_e32 v19, -16, v188
	v_cmp_lt_i32_e32 vcc, v19, v36
	v_readlane_b32 s22, v255, 24
	v_readlane_b32 s23, v255, 25
	v_cndmask_b32_e32 v19, v19, v188, vcc
	v_lshlrev_b32_e32 v19, 2, v19
	ds_bpermute_b32 v19, v19, v18
	s_waitcnt lgkmcnt(0)
	v_add_f32_e32 v19, v18, v19
	v_cndmask_b32_e64 v18, v19, v18, s[22:23]
	v_subrev_u32_e32 v19, 32, v188
	v_cmp_lt_i32_e32 vcc, v19, v36
	v_readlane_b32 s22, v255, 26
	v_readlane_b32 s23, v255, 27
	v_cndmask_b32_e32 v19, v19, v188, vcc
	v_lshlrev_b32_e32 v19, 2, v19
	ds_bpermute_b32 v19, v19, v18
	s_waitcnt lgkmcnt(0)
	v_add_f32_e32 v19, v18, v19
	v_cndmask_b32_e64 v18, v19, v18, s[22:23]
	v_lshl_or_b32 v19, v188, 2, v252
	ds_bpermute_b32 v19, v19, v18
	ds_write_b32 v69, v18
	ds_write_b32 v76, v16
	s_waitcnt lgkmcnt(2)
	v_sub_f32_e32 v18, v19, v18
	v_mul_f32_e32 v18, 0x3fb8aa3b, v18
	v_exp_f32_e32 v18, v18
	s_nop 0
	v_mul_f32_e32 v16, v16, v18
	ds_write_b32 v77, v16
	v_mul_f32_e32 v16, 0x3fb8aa3b, v19
	v_exp_f32_e32 v18, v16
	s_nop 0
	v_mov_b32_e32 v19, v18
	ds_write_b64 v108, v[18:19]

; __device__ __forceinline__ void mamba_block(ArgsP a_, unsigned char* smem) { const ArgsP a = a_;
;     ...
;         if (tid < 64) { const int j = tid; const bool valid = j < len; const float dtr = dtpre + AIN(22)[hd];
;             const float dt = valid ? (dtr > 20.f ? dtr : log1pf(__expf(dtr))) : 0.f; float x = -dt * __expf(AIN(23)[hd]);
.LBB0_353:
	s_lshl_b32 s22, s76, 6
	v_add_u32_e32 v0, s93, v85
	s_and_b32 s74, s22, 0x700
	s_mov_b32 s75, s12
	v_ashrrev_i32_e32 v1, 31, v0
	v_lshl_add_u64 v[8:9], v[60:61], 0, s[74:75]
	v_lshlrev_b64 v[0:1], 13, v[0:1]
	v_add_u32_e32 v10, s93, v73
	v_lshl_add_u64 v[0:1], v[8:9], 0, v[0:1]
	v_ashrrev_i32_e32 v11, 31, v10
	s_and_b32 s64, s76, 31
	v_add_co_u32_e32 v4, vcc, 0x1000, v0
	v_lshlrev_b64 v[10:11], 13, v[10:11]
	v_add_u32_e32 v18, s93, v78
	v_addc_co_u32_e32 v5, vcc, 0, v1, vcc
	v_lshl_add_u64 v[8:9], v[8:9], 0, v[10:11]
	s_lshl_b32 s76, s64, 7
	s_mov_b32 s77, s12
	v_ashrrev_i32_e32 v19, 31, v18
	v_add_co_u32_e32 v12, vcc, 0x1000, v8
	v_lshl_add_u64 v[40:41], v[62:63], 0, s[76:77]
	v_lshlrev_b64 v[18:19], 13, v[18:19]
	v_addc_co_u32_e32 v13, vcc, 0, v9, vcc
	v_lshl_add_u64 v[18:19], v[40:41], 0, v[18:19]
	global_load_dwordx4 v[0:3], v[4:5], off
	s_nop 0
	global_load_dwordx4 v[4:7], v[4:5], off offset:2048
	s_nop 0
	global_load_dwordx4 v[8:11], v[12:13], off
	s_nop 0
	global_load_dwordx4 v[12:15], v[12:13], off offset:2048
	v_add_u32_e32 v36, s93, v88
	global_load_ushort v115, v[18:19], off
	v_add_u32_e32 v18, s93, v86
	v_ashrrev_i32_e32 v19, 31, v18
	v_ashrrev_i32_e32 v37, 31, v36
	v_lshlrev_b64 v[18:19], 13, v[18:19]
	v_lshlrev_b64 v[36:37], 13, v[36:37]
	v_lshl_add_u64 v[18:19], v[40:41], 0, v[18:19]
	v_lshl_add_u64 v[36:37], v[40:41], 0, v[36:37]
	global_load_ushort v116, v[18:19], off
	v_add_u32_e32 v38, s93, v92
	global_load_ushort v117, v[36:37], off
	v_add_u32_e32 v36, s93, v90
	v_ashrrev_i32_e32 v37, 31, v36
	v_ashrrev_i32_e32 v39, 31, v38
	v_lshlrev_b64 v[36:37], 13, v[36:37]
	v_lshlrev_b64 v[38:39], 13, v[38:39]
	v_lshl_add_u64 v[36:37], v[40:41], 0, v[36:37]
	v_lshl_add_u64 v[38:39], v[40:41], 0, v[38:39]
	global_load_ushort v120, v[36:37], off
	v_add_u32_e32 v42, s93, v96
	global_load_ushort v118, v[38:39], off
	v_add_u32_e32 v38, s93, v94
	v_ashrrev_i32_e32 v39, 31, v38
	v_ashrrev_i32_e32 v43, 31, v42
	v_lshlrev_b64 v[38:39], 13, v[38:39]
	v_lshlrev_b64 v[42:43], 13, v[42:43]
	v_lshl_add_u64 v[38:39], v[40:41], 0, v[38:39]
	v_lshl_add_u64 v[42:43], v[40:41], 0, v[42:43]
	global_load_ushort v119, v[38:39], off
	global_load_ushort v121, v[42:43], off
	v_add_u32_e32 v42, s93, v98
	v_ashrrev_i32_e32 v43, 31, v42
	v_lshlrev_b64 v[42:43], 13, v[42:43]
	v_lshl_add_u64 v[40:41], v[40:41], 0, v[42:43]
	global_load_ushort v122, v[40:41], off
	s_and_saveexec_b64 s[96:97], s[40:41]
	s_cbranch_execz .LBB0_355
	v_add_u32_e32 v42, s93, v57
	v_ashrrev_i32_e32 v43, 31, v42
	v_readlane_b32 s22, v255, 28
	v_lshlrev_b64 v[42:43], 10, v[42:43]
	v_readlane_b32 s23, v255, 29
	s_nop 1
	v_lshl_add_u64 v[42:43], s[22:23], 0, v[42:43]
	s_lshl_b32 s22, s64, 2
	s_mov_b32 s23, s12
	v_lshl_add_u64 v[42:43], v[42:43], 0, s[22:23]
	global_load_dword v67, v[42:43], off
	s_load_dwordx4 s[84:87], s[4:5], 0xb0
	s_lshl_b32 s22, s64, 2
	v_mov_b32_e32 v42, s22
	s_waitcnt lgkmcnt(0)
	global_load_dword v128, v42, s[84:85]
	global_load_dword v129, v42, s[86:87]

; __device__ __forceinline__ unsigned xb_ld(unsigned* p)              { return __hip_atomic_load(p, __ATOMIC_RELAXED, __HIP_MEMORY_SCOPE_AGENT); }
; __device__ __forceinline__ unsigned xb_add(unsigned* p, unsigned v) { return __hip_atomic_fetch_add(p, v, __ATOMIC_RELAXED, __HIP_MEMORY_SCOPE_AGENT); }
; #define XB_SPIN(cond, bar) do { unsigned _sp = 0; while (cond) { __builtin_amdgcn_s_sleep(1); \
;     if ((++_sp & 255u) == 0u) { if (xb_ld(&(bar)[XB_TMO])) break; if (_sp > XB_SPIN_CAP) { atomicAdd(&(bar)[XB_TMO], 1u); break; } } } } while (0)
; __device__ __forceinline__ void xcd_barrier(const XcdBarrier& b) {
;     ...
;         unsigned nloc = b.st[0], nx = b.st[1];
;         if (nloc == 0u) { xcd_barrier_complete(bar, b.x, nloc, nx); b.st[0] = nloc; b.st[1] = nx; }
;         const unsigned old = xb_add(&bar[XB_XSUB(b.x)], 1u);
;         const unsigned gen = old / nloc;
;         if (old + 1u == (gen + 1u) * nloc) {
;             __builtin_amdgcn_fence(__ATOMIC_RELEASE, "agent");
;             asm volatile("s_waitcnt vmcnt(0)" ::: "memory");
;             const unsigned og = xb_add(&bar[XB_TOP], 1u);
;             const unsigned tg = og / nx;
;             if (og + 1u == (tg + 1u) * nx) xb_add(&bar[XB_TOPGEN], 1u);
;             else XB_SPIN(xb_ld(&bar[XB_TOPGEN]) == tg, bar);
;             __builtin_amdgcn_fence(__ATOMIC_ACQUIRE, "agent");
;             xb_add(&bar[XB_XGEN(b.x)], 1u);
;             asm volatile("s_waitcnt vmcnt(0)" ::: "memory");
;         } else {
;             XB_SPIN(xb_ld(&bar[XB_XGEN(b.x)]) == gen, bar);
;             __builtin_amdgcn_fence(__ATOMIC_ACQUIRE, "agent");
;             asm volatile("s_waitcnt vmcnt(0)" ::: "memory");
.LBB0_1005:
	s_or_b64 exec, exec, s[2:3]
	v_cvt_f32_u32_e32 v4, v2
	s_waitcnt vmcnt(0)
	buffer_inv sc1
	v_readfirstlane_b32 s2, v3
	v_sub_u32_e32 v3, 0, v2
	v_rcp_iflag_f32_e32 v4, v4
	v_add_u32_e32 v5, s2, v1
	v_mul_f32_e32 v4, 0x4f7ffffe, v4
	v_cvt_u32_f32_e32 v4, v4
	v_mul_lo_u32 v1, v3, v4
	v_mul_hi_u32 v1, v4, v1
	v_add_u32_e32 v1, v4, v1
	v_mul_hi_u32 v1, v5, v1
	v_mul_lo_u32 v3, v1, v2
	v_sub_u32_e32 v3, v5, v3
	v_add_u32_e32 v4, 1, v1
	v_cmp_ge_u32_e32 vcc, v3, v2
	s_nop 1
	v_cndmask_b32_e32 v1, v1, v4, vcc
	v_sub_u32_e32 v4, v3, v2
	v_cndmask_b32_e32 v3, v3, v4, vcc
	v_add_u32_e32 v4, 1, v1
	v_cmp_ge_u32_e32 vcc, v3, v2
	v_add_u32_e32 v3, 1, v5
	s_nop 0
	v_cndmask_b32_e32 v1, v1, v4, vcc
	v_mul_lo_u32 v4, v2, v1
	v_add_u32_e32 v2, v4, v2
	v_cmp_ne_u32_e32 vcc, v3, v2
	s_and_saveexec_b64 s[2:3], vcc
	s_xor_b64 s[2:3], exec, s[2:3]
	s_cbranch_execz .LBB0_1019
	v_readlane_b32 s4, v254, 13
	v_readlane_b32 s5, v254, 14
	s_waitcnt lgkmcnt(0)
	s_nop 3
	global_load_dword v0, v17, s[4:5] sc1
	s_waitcnt vmcnt(0)
	v_cmp_eq_u32_e32 vcc, v0, v1
	s_and_saveexec_b64 s[4:5], vcc
	s_cbranch_execz .LBB0_1018
	s_mov_b32 s40, 1
	s_mov_b64 s[18:19], 0
	s_branch .LBB0_1009

; __device__ __forceinline__ unsigned xb_ld(unsigned* p)              { return __hip_atomic_load(p, __ATOMIC_RELAXED, __HIP_MEMORY_SCOPE_AGENT); }
; #define XB_SPIN(cond, bar) do { unsigned _sp = 0; while (cond) { __builtin_amdgcn_s_sleep(1); \
;     if ((++_sp & 255u) == 0u) { if (xb_ld(&(bar)[XB_TMO])) break; if (_sp > XB_SPIN_CAP) { atomicAdd(&(bar)[XB_TMO], 1u); break; } } } } while (0)
; __device__ __forceinline__ void xcd_barrier(const XcdBarrier& b) {
;     ...
;             XB_SPIN(xb_ld(&bar[XB_XGEN(b.x)]) == gen, bar);
;             __builtin_amdgcn_fence(__ATOMIC_ACQUIRE, "agent");
;             asm volatile("s_waitcnt vmcnt(0)" ::: "memory");
.LBB0_1018:
	s_or_b64 exec, exec, s[4:5]
	s_waitcnt vmcnt(0)
	s_waitcnt vmcnt(0)

; __device__ __forceinline__ unsigned xb_ld(unsigned* p)              { return __hip_atomic_load(p, __ATOMIC_RELAXED, __HIP_MEMORY_SCOPE_AGENT); }
; __device__ __forceinline__ unsigned xb_add(unsigned* p, unsigned v) { return __hip_atomic_fetch_add(p, v, __ATOMIC_RELAXED, __HIP_MEMORY_SCOPE_AGENT); }
; #define XB_SPIN(cond, bar) do { unsigned _sp = 0; while (cond) { __builtin_amdgcn_s_sleep(1); \
;     if ((++_sp & 255u) == 0u) { if (xb_ld(&(bar)[XB_TMO])) break; if (_sp > XB_SPIN_CAP) { atomicAdd(&(bar)[XB_TMO], 1u); break; } } } } while (0)
; __device__ __forceinline__ void xcd_barrier(const XcdBarrier& b) {
;     ...
;             if (og + 1u == (tg + 1u) * nx) xb_add(&bar[XB_TOPGEN], 1u);
;             else XB_SPIN(xb_ld(&bar[XB_TOPGEN]) == tg, bar);
;             __builtin_amdgcn_fence(__ATOMIC_ACQUIRE, "agent");
;             xb_add(&bar[XB_XGEN(b.x)], 1u);
;             asm volatile("s_waitcnt vmcnt(0)" ::: "memory");
.LBB0_1037:
	s_or_b64 exec, exec, s[2:3]
	s_mov_b64 s[2:3], exec
	v_mbcnt_lo_u32_b32 v0, s2, 0
	v_mbcnt_hi_u32_b32 v0, s3, v0
	v_cmp_eq_u32_e32 vcc, 0, v0
	s_waitcnt vmcnt(0)
	s_and_saveexec_b64 s[4:5], vcc
	s_cbranch_execz .LBB0_1039
	s_bcnt1_i32_b64 s2, s[2:3]
	v_mov_b32_e32 v0, s2
	v_readlane_b32 s2, v254, 13
	v_readlane_b32 s3, v254, 14
	s_nop 4
	global_atomic_add v17, v0, s[2:3]
